# nt cache policy: P0 x/p row loads and P1 in-proj epilogue stores non-temporal
# speedup vs baseline: 1.0419x; 1.0419x over previous
; #define P0_LOADROW(buf, mm) do { const int m_ = (mm); if (m_ < M) { const float* xr_ = m_ < MP ? P.x_p + (size_t)m_ * 1024 : P.x_s + (size_t)(m_ - MP) * 1024; \
;         _Pragma("unroll") for (int j = 0; j < 4; ++j) buf[j] = ((const f32x4*)xr_)[64 * j + lane]; } } while (0)
; __device__ __forceinline__ void phase0(const Params& P, LAS unsigned char* lds, int tid, int lane, int wave, int G) {
;     ...
;     f32x4 lg[4];
; #pragma unroll
;     for (int j = 0; j < 4; ++j) lg[j] = ((const f32x4*)P.ln_g)[64 * j + lane];
;     bf16* XN = (bf16*)(ws + WS_XN);
;     f32x4 rb0[4], rb1[4], rb2[4];
;     ...
;     P0_LOADROW(rb0, gw); P0_LOADROW(rb1, gw + NGW); P0_LOADROW(rb2, gw + 2 * NGW);
.LBB0_45:
	s_or_b64 exec, exec, s[26:27]
	v_readlane_b32 s8, v247, 7
	v_lshlrev_b32_e32 v1, 4, v68
	v_readlane_b32 s9, v247, 8
	s_nop 4
	global_load_dwordx4 v[2:5], v1, s[8:9]
	global_load_dwordx4 v[6:9], v1, s[8:9] offset:1024
	global_load_dwordx4 v[10:13], v1, s[8:9] offset:2048
	global_load_dwordx4 v[14:17], v1, s[8:9] offset:3072
	s_cmp_lt_i32 s6, 0x10100
	v_mov_b32_e32 v18, 0
	s_cselect_b64 s[0:1], -1, 0
	s_and_b64 vcc, exec, s[0:1]
	v_mov_b32_e32 v19, v18
	v_mov_b32_e32 v20, v18
	v_mov_b32_e32 v21, v18
	v_mov_b32_e32 v22, v18
	v_mov_b32_e32 v23, v18
	v_mov_b32_e32 v24, v18
	v_mov_b32_e32 v25, v18
	v_mov_b32_e32 v26, v18
	v_mov_b32_e32 v27, v18
	v_mov_b32_e32 v28, v18
	v_mov_b32_e32 v29, v18
	v_mov_b32_e32 v30, v18
	v_mov_b32_e32 v31, v18
	v_mov_b32_e32 v32, v18
	v_mov_b32_e32 v33, v18
	v_readlane_b32 s10, v247, 9
	v_readlane_b32 s11, v247, 10
	v_readlane_b32 s12, v247, 11
	v_readlane_b32 s13, v247, 12
	v_readlane_b32 s14, v247, 13
	v_readlane_b32 s15, v247, 14
	v_readlane_b32 s16, v247, 15
	v_readlane_b32 s17, v247, 16
	v_readlane_b32 s18, v247, 17
	v_readlane_b32 s19, v247, 18
	v_readlane_b32 s20, v247, 19
	v_readlane_b32 s21, v247, 20
	v_readlane_b32 s22, v247, 21
	v_readlane_b32 s23, v247, 22
	s_cbranch_vccz .LBB0_47
	s_add_i32 s7, s6, 0xffff0000
	s_ashr_i32 s8, s6, 31
	s_cmp_lt_i32 s6, 0x10000
	s_cselect_b32 s9, s8, 0
	s_cselect_b32 s8, s6, s7
	s_cselect_b32 s7, s69, s71
	s_cselect_b32 s10, s68, s70
	s_lshl_b64 s[8:9], s[8:9], 12
	s_add_u32 s8, s10, s8
	s_addc_u32 s9, s7, s9
	global_load_dwordx4 v[18:21], v1, s[8:9] nt
	global_load_dwordx4 v[22:25], v1, s[8:9] offset:1024 nt
	global_load_dwordx4 v[26:29], v1, s[8:9] offset:2048 nt
	global_load_dwordx4 v[30:33], v1, s[8:9] offset:3072 nt
.LBB0_47:
	s_add_i32 s7, s6, s2
	s_cmp_gt_i32 s7, 0x100ff
	s_cbranch_scc1 .LBB0_49
	s_add_i32 s8, s7, 0xffff0000
	s_ashr_i32 s9, s7, 31
	s_cmp_lt_i32 s7, 0x10000
	s_cselect_b32 s9, s9, 0
	s_cselect_b32 s8, s7, s8
	s_cselect_b32 s10, s69, s71
	s_cselect_b32 s11, s68, s70
	s_lshl_b64 s[8:9], s[8:9], 12
	s_add_u32 s8, s11, s8
	s_addc_u32 s9, s10, s9
	global_load_dwordx4 v[34:37], v1, s[8:9] nt
	global_load_dwordx4 v[38:41], v1, s[8:9] offset:1024 nt
	global_load_dwordx4 v[42:45], v1, s[8:9] offset:2048 nt
	global_load_dwordx4 v[46:49], v1, s[8:9] offset:3072 nt
.LBB0_49:
	s_add_i32 s7, s7, s2
	s_cmp_gt_i32 s7, 0x100ff
	s_cbranch_scc1 .LBB0_51
	s_add_i32 s8, s7, 0xffff0000
	s_ashr_i32 s9, s7, 31
	s_cmp_lt_i32 s7, 0x10000
	s_cselect_b32 s9, s9, 0
	s_cselect_b32 s8, s7, s8
	s_cselect_b32 s7, s69, s71
	s_cselect_b32 s10, s68, s70
	s_lshl_b64 s[8:9], s[8:9], 12
	s_add_u32 s8, s10, s8
	s_addc_u32 s9, s7, s9
	global_load_dwordx4 v[50:53], v1, s[8:9] nt
	global_load_dwordx4 v[54:57], v1, s[8:9] offset:1024 nt
	global_load_dwordx4 v[58:61], v1, s[8:9] offset:2048 nt
	global_load_dwordx4 v[62:65], v1, s[8:9] offset:3072 nt
	s_andn2_b64 vcc, exec, s[0:1]
	s_cbranch_vccnz .LBB0_78
	s_branch .LBB0_52

; #define P0_LOADROW(buf, mm) do { const int m_ = (mm); if (m_ < M) { const float* xr_ = m_ < MP ? P.x_p + (size_t)m_ * 1024 : P.x_s + (size_t)(m_ - MP) * 1024; \
;         _Pragma("unroll") for (int j = 0; j < 4; ++j) buf[j] = ((const f32x4*)xr_)[64 * j + lane]; } } while (0)
; __device__ __forceinline__ void phase0(const Params& P, LAS unsigned char* lds, int tid, int lane, int wave, int G) {
;     ...
;     P0_LOADROW(rb0, gw); P0_LOADROW(rb1, gw + NGW); P0_LOADROW(rb2, gw + 2 * NGW);
;     for (int m = gw; m < M; m += 3 * NGW) {
;         P0_DOROW(rb0, m);           P0_LOADROW(rb0, m + 3 * NGW);
;         P0_DOROW(rb1, m + NGW);     P0_LOADROW(rb1, m + 4 * NGW);
;         P0_DOROW(rb2, m + 2 * NGW); P0_LOADROW(rb2, m + 5 * NGW);
.LBB0_54:
	s_waitcnt vmcnt(3)
	v_pk_mul_f32 v[84:85], v[20:21], v[20:21]
	v_pk_mul_f32 v[86:87], v[18:19], v[18:19]
	s_waitcnt vmcnt(2)
	v_pk_mul_f32 v[80:81], v[24:25], v[24:25]
	v_pk_mul_f32 v[82:83], v[22:23], v[22:23]
	v_pk_mov_b32 v[88:89], v[86:87], v[84:85] op_sel:[1,0]
	v_mov_b32_e32 v87, v85
	v_pk_add_f32 v[84:85], v[88:89], v[86:87]
	v_pk_mov_b32 v[86:87], v[82:83], v[80:81] op_sel:[1,0]
	v_mov_b32_e32 v83, v81
	v_pk_add_f32 v[80:81], v[86:87], v[82:83]
	v_pk_add_f32 v[84:85], v[84:85], v[84:85] op_sel_hi:[0,1]
	v_pk_add_f32 v[80:81], v[80:81], v[80:81] op_sel_hi:[0,1]
	s_waitcnt vmcnt(1)
	v_mul_f32_e32 v80, v26, v26
	v_pk_fma_f32 v[82:83], v[26:27], v[26:27], v[80:81] op_sel_hi:[1,1,0]
	v_mul_f32_e32 v80, v28, v28
	v_pk_fma_f32 v[86:87], v[28:29], v[28:29], v[80:81] op_sel_hi:[1,1,0]
	s_waitcnt vmcnt(0)
	v_mul_f32_e32 v82, v30, v30
	v_mul_f32_e32 v86, v31, v31
	v_mul_f32_e32 v84, v32, v32
	v_mul_f32_e32 v80, v33, v33
	v_pk_add_f32 v[82:83], v[82:83], v[86:87]
	v_pk_add_f32 v[80:81], v[84:85], v[80:81]
	s_add_i32 s7, s30, s34
	v_pk_add_f32 v[80:81], v[82:83], v[80:81]
	s_cmp_lt_i32 s7, 0x10100
	v_add_f32_e32 v79, v80, v81
	ds_bpermute_b32 v80, v67, v79
	s_waitcnt lgkmcnt(0)
	v_add_f32_e32 v79, v79, v80
	ds_bpermute_b32 v80, v74, v79
	s_waitcnt lgkmcnt(0)
	v_add_f32_e32 v79, v79, v80
	ds_bpermute_b32 v80, v75, v79
	s_waitcnt lgkmcnt(0)
	v_add_f32_e32 v79, v79, v80
	ds_bpermute_b32 v80, v76, v79
	s_waitcnt lgkmcnt(0)
	v_add_f32_e32 v79, v79, v80
	ds_bpermute_b32 v80, v77, v79
	s_waitcnt lgkmcnt(0)
	v_add_f32_e32 v79, v79, v80
	ds_bpermute_b32 v80, v78, v79
	s_waitcnt lgkmcnt(0)
	v_add_f32_e32 v79, v79, v80
	v_fmamk_f32 v79, v79, 0x3a800000, v69
	v_rsq_f32_e32 v80, v79
	s_nop 0
	v_pk_mul_f32 v[82:83], v[18:19], v[80:81] op_sel_hi:[1,0]
	v_pk_mul_f32 v[84:85], v[20:21], v[80:81] op_sel_hi:[1,0]
	v_pk_mul_f32 v[86:87], v[22:23], v[80:81] op_sel_hi:[1,0]
	v_pk_mul_f32 v[88:89], v[24:25], v[80:81] op_sel_hi:[1,0]
	v_pk_mul_f32 v[84:85], v[4:5], v[84:85]
	v_pk_mul_f32 v[82:83], v[2:3], v[82:83]
	v_pk_mul_f32 v[88:89], v[8:9], v[88:89]
	v_pk_mul_f32 v[86:87], v[6:7], v[86:87]
	v_cvt_pk_bf16_f32 v82, v82, v83
	v_cvt_pk_bf16_f32 v83, v84, v85
	v_pk_mul_f32 v[90:91], v[26:27], v[80:81] op_sel_hi:[1,0]
	v_cvt_pk_bf16_f32 v84, v86, v87
	v_cvt_pk_bf16_f32 v85, v88, v89
	global_store_dwordx2 v[72:73], v[82:83], off
	global_store_dwordx2 v[72:73], v[84:85], off offset:512
	v_pk_mul_f32 v[82:83], v[28:29], v[80:81] op_sel_hi:[1,0]
	v_pk_mul_f32 v[84:85], v[10:11], v[90:91]
	v_pk_mul_f32 v[82:83], v[12:13], v[82:83]
	v_cvt_pk_bf16_f32 v84, v84, v85
	v_cvt_pk_bf16_f32 v85, v82, v83
	v_pk_mul_f32 v[82:83], v[30:31], v[80:81] op_sel_hi:[1,0]
	v_pk_mul_f32 v[80:81], v[32:33], v[80:81] op_sel_hi:[1,0]
	v_pk_mul_f32 v[82:83], v[14:15], v[82:83]
	v_pk_mul_f32 v[80:81], v[16:17], v[80:81]
	v_cvt_pk_bf16_f32 v82, v82, v83
	v_cvt_pk_bf16_f32 v83, v80, v81
	global_store_dwordx2 v[72:73], v[84:85], off offset:1024
	global_store_dwordx2 v[72:73], v[82:83], off offset:1536
	s_cbranch_scc0 .LBB0_59
	s_add_i32 s10, s7, 0xffff0000
	s_cmp_lt_i32 s7, 0x10000
	s_cselect_b32 s11, s35, 0
	s_cselect_b32 s10, s31, s10
	s_cselect_b32 s7, s69, s71
	s_cselect_b32 s12, s68, s70
	s_lshl_b64 s[10:11], s[10:11], 12
	s_add_u32 s10, s12, s10
	s_addc_u32 s11, s7, s11
	global_load_dwordx4 v[18:21], v1, s[10:11] nt
	global_load_dwordx4 v[22:25], v1, s[10:11] offset:1024 nt
	global_load_dwordx4 v[26:29], v1, s[10:11] offset:2048 nt
	global_load_dwordx4 v[30:33], v1, s[10:11] offset:3072 nt
	s_add_i32 s10, s26, s34
	s_cmp_gt_i32 s10, 0x100ff
	s_cbranch_scc0 .LBB0_60

; #define P0_LOADROW(buf, mm) do { const int m_ = (mm); if (m_ < M) { const float* xr_ = m_ < MP ? P.x_p + (size_t)m_ * 1024 : P.x_s + (size_t)(m_ - MP) * 1024; \
;         _Pragma("unroll") for (int j = 0; j < 4; ++j) buf[j] = ((const f32x4*)xr_)[64 * j + lane]; } } while (0)
; __device__ __forceinline__ void phase0(const Params& P, LAS unsigned char* lds, int tid, int lane, int wave, int G) {
;     ...
;     P0_LOADROW(rb0, gw); P0_LOADROW(rb1, gw + NGW); P0_LOADROW(rb2, gw + 2 * NGW);
;     for (int m = gw; m < M; m += 3 * NGW) {
;         P0_DOROW(rb0, m);           P0_LOADROW(rb0, m + 3 * NGW);
;         P0_DOROW(rb1, m + NGW);     P0_LOADROW(rb1, m + 4 * NGW);
.LBB0_57:
	s_add_i32 s10, s7, 0xffff0000
	s_ashr_i32 s11, s7, 31
	s_cmp_lt_i32 s7, 0x10000
	s_cselect_b32 s11, s11, 0
	s_cselect_b32 s10, s7, s10
	s_cselect_b32 s7, s69, s71
	s_cselect_b32 s12, s68, s70
	s_lshl_b64 s[10:11], s[10:11], 12
	s_add_u32 s10, s12, s10
	s_addc_u32 s11, s7, s11
	global_load_dwordx4 v[34:37], v1, s[10:11] nt
	global_load_dwordx4 v[38:41], v1, s[10:11] offset:1024 nt
	global_load_dwordx4 v[42:45], v1, s[10:11] offset:2048 nt
	global_load_dwordx4 v[46:49], v1, s[10:11] offset:3072 nt
	s_add_i32 s10, s28, s34
	s_cmp_gt_i32 s10, 0x100ff
	s_cbranch_scc0 .LBB0_62

; #define P0_LOADROW(buf, mm) do { const int m_ = (mm); if (m_ < M) { const float* xr_ = m_ < MP ? P.x_p + (size_t)m_ * 1024 : P.x_s + (size_t)(m_ - MP) * 1024; \
;         _Pragma("unroll") for (int j = 0; j < 4; ++j) buf[j] = ((const f32x4*)xr_)[64 * j + lane]; } } while (0)
; __device__ __forceinline__ void phase0(const Params& P, LAS unsigned char* lds, int tid, int lane, int wave, int G) {
;     ...
;     P0_LOADROW(rb0, gw); P0_LOADROW(rb1, gw + NGW); P0_LOADROW(rb2, gw + 2 * NGW);
;     for (int m = gw; m < M; m += 3 * NGW) {
;         P0_DOROW(rb0, m);           P0_LOADROW(rb0, m + 3 * NGW);
;         P0_DOROW(rb1, m + NGW);     P0_LOADROW(rb1, m + 4 * NGW);
;         P0_DOROW(rb2, m + 2 * NGW); P0_LOADROW(rb2, m + 5 * NGW);
.LBB0_63:
	s_add_i32 s10, s7, 0xffff0000
	s_ashr_i32 s11, s7, 31
	s_cmp_lt_i32 s7, 0x10000
	s_cselect_b32 s11, s11, 0
	s_cselect_b32 s10, s7, s10
	s_cselect_b32 s7, s69, s71
	s_cselect_b32 s12, s68, s70
	s_lshl_b64 s[10:11], s[10:11], 12
	s_add_u32 s10, s12, s10
	s_addc_u32 s11, s7, s11
	global_load_dwordx4 v[50:53], v1, s[10:11] nt
	global_load_dwordx4 v[54:57], v1, s[10:11] offset:1024 nt
	global_load_dwordx4 v[58:61], v1, s[10:11] offset:2048 nt
	global_load_dwordx4 v[62:65], v1, s[10:11] offset:3072 nt
	s_branch .LBB0_53

; __device__ __forceinline__ unsigned pk2(float lo, float hi) { return pg8::cvt_pk_bf16_v(lo, hi); }
; __device__ __forceinline__ void phase0(const Params& P, LAS unsigned char* lds, int tid, int lane, int wave, int G) {
;     ...
;     bf16* PB = (bf16*)(ws + WS_PB);
;     for (int m0 = gw; m0 < M; m0 += 4 * NGW) {
;         f32x4 pv[4];
; #pragma unroll
;         for (int k = 0; k < 4; ++k) { const int m = m0 + k * NGW; if (m < M) { const float* prow = m < MP ? P.p_p + (size_t)m * 256 : P.p_s + (size_t)(m - MP) * 256; pv[k] = ((const f32x4*)prow)[lane]; } }
; #pragma unroll
;         for (int k = 0; k < 4; ++k) { const int m = m0 + k * NGW; if (m < M) { v2u o; o.x = pk2(pv[k][0], pv[k][1]); o.y = pk2(pv[k][2], pv[k][3]); ((v2u*)(PB + (size_t)m * 256))[lane] = o; } }
;     }
.LBB0_66:
	s_add_i32 s1, s6, 0xffff0000
	s_ashr_i32 s7, s6, 31
	s_cmp_lt_i32 s6, 0x10000
	s_cselect_b32 s9, s7, 0
	s_cselect_b32 s8, s6, s1
	s_cselect_b32 s1, s81, s83
	s_cselect_b32 s10, s80, s82
	s_lshl_b64 s[8:9], s[8:9], 10
	s_add_u32 s8, s10, s8
	s_addc_u32 s9, s1, s9
	global_load_dwordx4 v[14:17], v1, s[8:9] nt
	s_add_i32 s8, s6, s2
	s_cmp_lt_i32 s8, 0x10100
	s_cselect_b64 s[26:27], -1, 0
	s_cmp_gt_i32 s8, 0x100ff
	s_cbranch_scc1 .LBB0_68
	s_ashr_i32 s1, s8, 31
	s_add_i32 s9, s8, 0xffff0000
	s_cmp_lt_i32 s8, 0x10000
	s_cselect_b32 s11, s1, 0
	s_cselect_b32 s10, s8, s9
	s_cselect_b32 s1, s81, s83
	s_cselect_b32 s9, s80, s82
	s_lshl_b64 s[10:11], s[10:11], 10
	s_add_u32 s10, s9, s10
	s_addc_u32 s11, s1, s11
	global_load_dwordx4 v[10:13], v1, s[10:11] nt
.LBB0_68:
	s_add_i32 s10, s25, s6
	s_cmp_lt_i32 s10, 0x10100
	s_cselect_b64 s[30:31], -1, 0
	s_cmp_gt_i32 s10, 0x100ff
	s_cbranch_scc1 .LBB0_70
	s_ashr_i32 s1, s10, 31
	s_add_i32 s9, s10, 0xffff0000
	s_cmp_lt_i32 s10, 0x10000
	s_cselect_b32 s29, s1, 0
	s_cselect_b32 s28, s10, s9
	s_cselect_b32 s1, s81, s83
	s_cselect_b32 s9, s80, s82
	s_lshl_b64 s[28:29], s[28:29], 10
	s_add_u32 s28, s9, s28
	s_addc_u32 s29, s1, s29
	global_load_dwordx4 v[6:9], v1, s[28:29] nt
.LBB0_70:
	s_add_i32 s28, s0, s6
	s_cmp_lt_i32 s28, 0x10100
	s_cselect_b64 s[34:35], -1, 0
	s_cmp_gt_i32 s28, 0x100ff
	s_cbranch_scc1 .LBB0_72
	s_ashr_i32 s1, s28, 31
	s_add_i32 s9, s28, 0xffff0000
	s_cmp_lt_i32 s28, 0x10000
	s_cselect_b32 s37, s1, 0
	s_cselect_b32 s36, s28, s9
	s_cselect_b32 s1, s81, s83
	s_cselect_b32 s9, s80, s82
	s_lshl_b64 s[36:37], s[36:37], 10
	s_add_u32 s36, s9, s36
	s_addc_u32 s37, s1, s37
	global_load_dwordx4 v[2:5], v1, s[36:37] nt

; #define PG8_LAS __attribute__((address_space(3)))
; __device__ __forceinline__ unsigned cvt_pk_bf16(float lo, float hi) { unsigned r; asm volatile("v_cvt_pk_bf16_f32 %0, %1, %2" : "=v"(r) : "v"(lo), "v"(hi)); return r; }
;     __device__ __forceinline__ void operator()(const f32x4 (&acc)[2][2][4][2], const Unit& u_, int wr, int wc, int fr, int fq) const {
;     ...
;         const int l = fq * 16 + fr; PG8_LAS unsigned char* xl = xl0 + (wr * 4 + wc) * XCHG_WAVE_BYTES;
;         const int rowb = u.pm * BM + wr * 64 + (l >> 2); const int colb = colt + wc * 32 + 8 * (l & 3);
; #pragma unroll
;         for (int ai = 0; ai < 2; ++ai)
; #pragma unroll
;             for (int m = 0; m < 4; ++m) { bf16_t* rowp = base + (size_t)(rowb + ai * HALF + m * 16) * ldc + colb;
; #pragma unroll
;                 for (int bj = 0; bj < 2; ++bj) { const f32x4 v0 = acc[ai][bj][m][0], v1 = acc[ai][bj][m][1];
;                     u32x4 w; w.x = cvt_pk_bf16(v0[0], v0[1]); w.y = cvt_pk_bf16(v0[2], v0[3]); w.z = cvt_pk_bf16(v1[0], v1[1]); w.w = cvt_pk_bf16(v1[2], v1[3]);
;                     *(u32x4*)(rowp + bj * HALF) = xchg_bf16(xl, fr, fq, l, w); } }
.LBB0_263:
	v_cvt_pk_bf16_f32 v126, v126, v127
	v_cvt_pk_bf16_f32 v127, v128, v129
	v_cvt_pk_bf16_f32 v128, v122, v123
	v_cvt_pk_bf16_f32 v129, v124, v125
	ds_write_b128 v159, v[126:129]
	v_lshl_add_u32 v161, s43, 8, v157
	ds_read_b128 v[122:125], v160
	v_add_u32_e32 v152, s2, v156
	v_ashrrev_i32_e32 v162, 31, v161
	v_ashrrev_i32_e32 v153, 31, v152
	v_mul_lo_u32 v162, s56, v162
	v_mul_lo_u32 v163, s57, v161
	v_mad_u64_u32 v[126:127], s[12:13], s56, v161, 0
	v_lshl_add_u64 v[152:153], v[152:153], 1, s[58:59]
	v_add3_u32 v127, v127, v162, v163
	v_lshl_add_u64 v[126:127], v[126:127], 1, v[152:153]
	s_waitcnt lgkmcnt(0)
	global_store_dwordx4 v[126:127], v[122:125], off nt
	v_cvt_pk_bf16_f32 v118, v118, v119
	v_cvt_pk_bf16_f32 v119, v120, v121
	v_cvt_pk_bf16_f32 v120, v110, v111
	v_cvt_pk_bf16_f32 v121, v112, v113
	ds_write_b128 v159, v[118:121]
	ds_read_b128 v[110:113], v160
	v_or_b32_e32 v118, 16, v161
	v_mul_lo_u32 v119, s57, v118
	s_andn2_b64 vcc, exec, s[0:1]
	s_mov_b64 s[0:1], -1
	s_waitcnt lgkmcnt(0)
	global_store_dwordx4 v[126:127], v[110:113], off offset:256 nt
	s_nop 1
	v_cvt_pk_bf16_f32 v110, v114, v115
	v_cvt_pk_bf16_f32 v111, v116, v117
	v_cvt_pk_bf16_f32 v112, v106, v107
	v_cvt_pk_bf16_f32 v113, v108, v109
	ds_write_b128 v159, v[110:113]
	ds_read_b128 v[106:109], v160
	v_mad_u64_u32 v[110:111], s[12:13], s56, v118, 0
	v_add3_u32 v111, v111, v162, v119
	v_lshl_add_u64 v[110:111], v[110:111], 1, v[152:153]
	s_waitcnt lgkmcnt(0)
	global_store_dwordx4 v[110:111], v[106:109], off nt
	v_cvt_pk_bf16_f32 v102, v102, v103
	v_cvt_pk_bf16_f32 v103, v104, v105
	v_cvt_pk_bf16_f32 v104, v94, v95
	v_cvt_pk_bf16_f32 v105, v96, v97
	ds_write_b128 v159, v[102:105]
	ds_read_b128 v[94:97], v160
	v_or_b32_e32 v102, 32, v161
	v_mul_lo_u32 v103, s57, v102
	s_waitcnt lgkmcnt(0)
	global_store_dwordx4 v[110:111], v[94:97], off offset:256 nt
	s_nop 1
	v_cvt_pk_bf16_f32 v94, v98, v99
	v_cvt_pk_bf16_f32 v95, v100, v101
	v_cvt_pk_bf16_f32 v96, v90, v91
	v_cvt_pk_bf16_f32 v97, v92, v93
	ds_write_b128 v159, v[94:97]
	ds_read_b128 v[90:93], v160
	v_mad_u64_u32 v[94:95], s[12:13], s56, v102, 0
	v_add3_u32 v95, v95, v162, v103
	v_lshl_add_u64 v[94:95], v[94:95], 1, v[152:153]
	s_waitcnt lgkmcnt(0)
	global_store_dwordx4 v[94:95], v[90:93], off nt
	v_cvt_pk_bf16_f32 v86, v86, v87
	v_cvt_pk_bf16_f32 v87, v88, v89
	v_cvt_pk_bf16_f32 v88, v78, v79
	v_cvt_pk_bf16_f32 v89, v80, v81
	ds_write_b128 v159, v[86:89]
	ds_read_b128 v[78:81], v160
	v_or_b32_e32 v86, 48, v161
	v_mul_lo_u32 v87, s57, v86
	s_waitcnt lgkmcnt(0)
	global_store_dwordx4 v[94:95], v[78:81], off offset:256 nt
	s_nop 1
	v_cvt_pk_bf16_f32 v78, v82, v83
	v_cvt_pk_bf16_f32 v79, v84, v85
	v_cvt_pk_bf16_f32 v80, v74, v75
	v_cvt_pk_bf16_f32 v81, v76, v77
	ds_write_b128 v159, v[78:81]
	ds_read_b128 v[74:77], v160
	v_mad_u64_u32 v[78:79], s[12:13], s56, v86, 0
	v_add3_u32 v79, v79, v162, v87
	v_lshl_add_u64 v[78:79], v[78:79], 1, v[152:153]
	s_waitcnt lgkmcnt(0)
	global_store_dwordx4 v[78:79], v[74:77], off nt
	v_cvt_pk_bf16_f32 v70, v70, v71
	v_cvt_pk_bf16_f32 v71, v72, v73
	v_cvt_pk_bf16_f32 v72, v66, v67
	v_cvt_pk_bf16_f32 v73, v68, v69
	ds_write_b128 v159, v[70:73]
	ds_read_b128 v[66:69], v160
	s_waitcnt lgkmcnt(0)
	global_store_dwordx4 v[78:79], v[66:69], off offset:256 nt
	v_cvt_pk_bf16_f32 v62, v62, v63
	v_cvt_pk_bf16_f32 v63, v64, v65
	v_cvt_pk_bf16_f32 v64, v58, v59
	v_cvt_pk_bf16_f32 v65, v60, v61
	ds_write_b128 v159, v[62:65]
	s_nop 0
	v_add_u32_e32 v66, 0x80, v161
	ds_read_b128 v[58:61], v160
	v_ashrrev_i32_e32 v67, 31, v66
	v_mul_lo_u32 v67, s56, v67
	v_mul_lo_u32 v68, s57, v66
	v_mad_u64_u32 v[62:63], s[12:13], s56, v66, 0
	v_add3_u32 v63, v63, v67, v68
	v_lshl_add_u64 v[62:63], v[62:63], 1, v[152:153]
	s_waitcnt lgkmcnt(0)
	global_store_dwordx4 v[62:63], v[58:61], off nt
	v_cvt_pk_bf16_f32 v54, v54, v55
	v_cvt_pk_bf16_f32 v55, v56, v57
	v_cvt_pk_bf16_f32 v56, v46, v47
	v_cvt_pk_bf16_f32 v57, v48, v49
	ds_write_b128 v159, v[54:57]
	ds_read_b128 v[46:49], v160
	v_add_u32_e32 v54, 0x90, v161
	v_mul_lo_u32 v56, s57, v54
	s_waitcnt lgkmcnt(0)
	global_store_dwordx4 v[62:63], v[46:49], off offset:256 nt
	s_nop 1
	v_ashrrev_i32_e32 v46, 31, v54
	v_mul_lo_u32 v55, s56, v46
	v_cvt_pk_bf16_f32 v46, v50, v51
	v_cvt_pk_bf16_f32 v47, v52, v53
	v_cvt_pk_bf16_f32 v48, v42, v43
	v_cvt_pk_bf16_f32 v49, v44, v45
	ds_write_b128 v159, v[46:49]
	ds_read_b128 v[42:45], v160
	v_mad_u64_u32 v[46:47], s[12:13], s56, v54, 0
	v_add3_u32 v47, v47, v55, v56
	v_lshl_add_u64 v[46:47], v[46:47], 1, v[152:153]
	s_waitcnt lgkmcnt(0)
	global_store_dwordx4 v[46:47], v[42:45], off nt
	v_cvt_pk_bf16_f32 v38, v38, v39
	v_cvt_pk_bf16_f32 v39, v40, v41
	v_cvt_pk_bf16_f32 v40, v30, v31
	v_cvt_pk_bf16_f32 v41, v32, v33
	ds_write_b128 v159, v[38:41]
	ds_read_b128 v[30:33], v160
	v_add_u32_e32 v38, 0xa0, v161
	v_mul_lo_u32 v40, s57, v38
	s_waitcnt lgkmcnt(0)
	global_store_dwordx4 v[46:47], v[30:33], off offset:256 nt
	s_nop 1
	v_ashrrev_i32_e32 v30, 31, v38
	v_mul_lo_u32 v39, s56, v30
	v_cvt_pk_bf16_f32 v30, v34, v35
	v_cvt_pk_bf16_f32 v31, v36, v37
	v_cvt_pk_bf16_f32 v32, v26, v27
	v_cvt_pk_bf16_f32 v33, v28, v29
	ds_write_b128 v159, v[30:33]
	ds_read_b128 v[26:29], v160
	v_mad_u64_u32 v[30:31], s[12:13], s56, v38, 0
	v_add3_u32 v31, v31, v39, v40
	v_lshl_add_u64 v[30:31], v[30:31], 1, v[152:153]
	s_waitcnt lgkmcnt(0)
	global_store_dwordx4 v[30:31], v[26:29], off nt
	v_cvt_pk_bf16_f32 v22, v22, v23
	v_cvt_pk_bf16_f32 v23, v24, v25
	v_cvt_pk_bf16_f32 v24, v14, v15
	v_cvt_pk_bf16_f32 v25, v16, v17
	ds_write_b128 v159, v[22:25]
	ds_read_b128 v[14:17], v160
	v_add_u32_e32 v22, 0xb0, v161
	v_mul_lo_u32 v24, s57, v22
	s_waitcnt lgkmcnt(0)
	global_store_dwordx4 v[30:31], v[14:17], off offset:256 nt
	s_nop 1
	v_ashrrev_i32_e32 v14, 31, v22
	v_mul_lo_u32 v23, s56, v14
	v_cvt_pk_bf16_f32 v14, v18, v19
	v_cvt_pk_bf16_f32 v15, v20, v21
	v_cvt_pk_bf16_f32 v16, v10, v11
	v_cvt_pk_bf16_f32 v17, v12, v13
	ds_write_b128 v159, v[14:17]
	ds_read_b128 v[10:13], v160
	v_mad_u64_u32 v[14:15], s[12:13], s56, v22, 0
	v_add3_u32 v15, v15, v23, v24
	v_lshl_add_u64 v[14:15], v[14:15], 1, v[152:153]
	s_waitcnt lgkmcnt(0)
	global_store_dwordx4 v[14:15], v[10:13], off nt
	v_cvt_pk_bf16_f32 v6, v6, v7
	v_cvt_pk_bf16_f32 v7, v8, v9
	v_cvt_pk_bf16_f32 v8, v2, v3
	v_cvt_pk_bf16_f32 v9, v4, v5
	ds_write_b128 v159, v[6:9]
	ds_read_b128 v[2:5], v160
	s_waitcnt lgkmcnt(0)
	global_store_dwordx4 v[14:15], v[2:5], off offset:256 nt
	s_cbranch_vccnz .LBB0_244
	s_andn2_b64 vcc, exec, s[4:5]
	s_cbranch_vccnz .LBB0_243
	s_barrier
	s_branch .LBB0_243
